# phase 4: context GLA-scan items moved off the workgroups running the long latent delta scans; delta-scan loop keeps outstanding memory ops bounded
# baseline (speedup 1.0000x reference)
.LBB0_170:
	v_readlane_b32 s0, v252, 2
	v_readlane_b32 s1, v252, 3
	s_load_dword s0, s[0:1], 0x0
	s_waitcnt lgkmcnt(0)
	s_add_i32 s13, s0, s13
	s_cmp_eq_u32 s0, 0x200
	s_cbranch_scc0 .Lp4_mv_done
	s_sub_u32 s0, s13, 0x200
	s_cmp_lt_u32 s0, 32
	s_cbranch_scc0 .Lp4_mv_1
	s_movk_i32 s13, 0x400
	s_branch .Lp4_mv_done
.Lp4_mv_1:
	s_sub_u32 s0, s13, 0x420
	s_cmp_lt_u32 s0, 32
	s_cbranch_scc0 .Lp4_mv_done
	s_add_u32 s13, s0, 0x200
.Lp4_mv_done:
	s_cmpk_gt_i32 s13, 0x33f
	s_cbranch_scc1 .LBB0_231

.LBB0_223:
	s_waitcnt vmcnt(0)
	s_add_i32 s36, s41, 0xe0000001
	s_and_b64 s[10:11], s[4:5], exec
	s_cselect_b32 s44, s45, s36
	s_add_i32 s43, s45, 1
	s_and_b64 s[10:11], s[4:5], exec
	s_cselect_b32 s10, s43, s41
	s_cmp_lt_u32 s43, s38
	s_cselect_b32 s10, s10, s44
	s_add_i32 s10, s10, s39
	s_lshl_b32 s10, s10, 3
	s_or_b32 s10, s10, s42
	v_mad_i64_i32 v[2:3], s[46:47], s10, v200, v[90:91]
	v_lshlrev_b32_e32 v130, 2, v26
	v_lshl_add_u64 v[4:5], v[2:3], 0, v[130:131]
	global_load_dword v113, v[4:5], off
	v_lshl_add_u64 v[4:5], v[56:57], 2, v[2:3]
	global_load_dword v114, v[4:5], off
	v_lshl_add_u64 v[4:5], v[54:55], 2, v[2:3]
	global_load_dword v115, v[4:5], off
	v_lshl_add_u64 v[4:5], v[52:53], 2, v[2:3]
	global_load_dword v116, v[4:5], off
	v_lshl_add_u64 v[4:5], v[50:51], 2, v[2:3]
	global_load_dword v117, v[4:5], off
	v_lshl_add_u64 v[4:5], v[48:49], 2, v[2:3]
	global_load_dword v118, v[4:5], off
	v_lshl_add_u64 v[4:5], v[46:47], 2, v[2:3]
	global_load_dword v119, v[4:5], off
	v_lshl_add_u64 v[4:5], v[44:45], 2, v[2:3]
	global_load_dword v121, v[4:5], off
	v_lshl_add_u64 v[4:5], v[42:43], 2, v[2:3]
	global_load_dword v122, v[4:5], off
	v_lshl_add_u64 v[4:5], v[40:41], 2, v[2:3]
	global_load_dword v124, v[4:5], off
	v_lshl_add_u64 v[4:5], v[38:39], 2, v[2:3]
	global_load_dword v127, v[4:5], off
	v_lshl_add_u64 v[4:5], v[36:37], 2, v[2:3]
	s_ashr_i32 s11, s10, 31
	global_load_dword v128, v[4:5], off
	v_lshl_add_u64 v[4:5], v[34:35], 2, v[2:3]
	s_lshl_b64 s[36:37], s[10:11], 2
	global_load_dword v129, v[4:5], off
	v_lshl_add_u64 v[4:5], v[32:33], 2, v[2:3]
	s_add_u32 s36, s86, s36
	global_load_dword v133, v[4:5], off
	v_lshl_add_u64 v[4:5], v[30:31], 2, v[2:3]
	v_lshl_add_u64 v[2:3], v[28:29], 2, v[2:3]
	s_addc_u32 s37, s87, s37
	global_load_dword v135, v[4:5], off
	global_load_dword v142, v[2:3], off
	global_load_dword v143, v131, s[36:37]
	s_cmp_ge_u32 s43, s38
	s_cbranch_scc1 .LBB0_225
	s_mul_hi_i32 s11, s10, 0xc000
	s_mul_i32 s10, s10, 0xc000
	s_add_u32 s10, s68, s10
	s_addc_u32 s11, s69, s11
	v_lshl_add_u64 v[2:3], s[10:11], 0, v[74:75]
	s_mov_b64 s[10:11], 0x4000
	v_lshl_add_u64 v[2:3], v[2:3], 0, s[10:11]
	s_add_i32 s10, s40, 0x8000
	s_and_b32 s10, s10, 0x8000
	v_add_u32_e32 v8, s10, v27
	v_add_u32_e32 v9, 0x400, v8
	v_readfirstlane_b32 s10, v8
	v_lshl_add_u64 v[4:5], v[2:3], 0, v[76:77]
	s_mov_b32 m0, s10
	v_readfirstlane_b32 s10, v9
	global_load_lds_dwordx4 v[4:5], off
	v_lshl_add_u64 v[6:7], v[4:5], 0, s[90:91]
	s_mov_b32 m0, s10
	s_mov_b64 s[10:11], 0x800
	v_add_u32_e32 v9, 0x800, v8
	global_load_lds_dwordx4 v[6:7], off
	v_lshl_add_u64 v[6:7], v[4:5], 0, s[10:11]
	v_readfirstlane_b32 s10, v9
	s_mov_b32 m0, s10
	s_mov_b64 s[10:11], 0xc00
	global_load_lds_dwordx4 v[6:7], off
	v_add_u32_e32 v6, 0xc00, v8
	v_lshl_add_u64 v[4:5], v[4:5], 0, s[10:11]
	v_readfirstlane_b32 s10, v6
	v_add_u32_e32 v6, 0x1000, v8
	s_mov_b32 m0, s10
	v_readfirstlane_b32 s10, v6
	v_add_u32_e32 v6, 0x1400, v8
	global_load_lds_dwordx4 v[4:5], off
	v_lshl_add_u64 v[4:5], v[2:3], 0, v[80:81]
	s_mov_b32 m0, s10
	v_readfirstlane_b32 s10, v6
	v_add_u32_e32 v6, 0x1800, v8
	global_load_lds_dwordx4 v[4:5], off
	v_lshl_add_u64 v[4:5], v[2:3], 0, v[82:83]
	s_mov_b32 m0, s10
	v_readfirstlane_b32 s10, v6
	global_load_lds_dwordx4 v[4:5], off
	v_lshl_add_u64 v[4:5], v[2:3], 0, v[84:85]
	s_mov_b32 m0, s10
	v_lshl_add_u64 v[2:3], v[2:3], 0, v[88:89]
	global_load_lds_dwordx4 v[4:5], off
	v_add_u32_e32 v4, 0x1c00, v8
	s_nop 0
	v_readfirstlane_b32 s10, v4
	s_mov_b32 m0, s10
	s_nop 0
	global_load_lds_dwordx4 v[2:3], off
